# LRU queue: next-unit atomic no longer waited right after issue
# baseline (speedup 1.0000x reference)
.LBB0_654:
	s_or_b64 exec, exec, s[0:1]
	v_mov_b32_e32 v252, v161
	v_mov_b32_e32 v253, 0
	v_and_b32_e32 v146, 48, v1
	v_mov_b32_e32 v147, 0
	v_lshl_add_u64 v[2:3], s[76:77], 0, v[146:147]
	s_mov_b64 s[0:1], 0x500000
	v_lshl_add_u64 v[148:149], v[2:3], 0, s[0:1]
	s_movk_i32 s0, 0x200
	v_cmp_gt_u32_e64 s[8:9], s0, v0
	s_movk_i32 s0, 0x210
	s_mov_b32 s61, 0
	v_and_b32_e32 v162, 0x70, v186
	v_mad_u32_u24 v2, v185, s0, 0
	v_lshlrev_b32_e32 v3, 8, v185
	s_add_u32 s24, s76, 0x300000
	v_lshl_add_u32 v167, v162, 2, v2
	v_sub_u32_e32 v2, v2, v3
	s_addc_u32 s25, s77, 0
	s_lshl_b64 s[0:1], s[60:61], 12
	v_lshl_add_u32 v168, v162, 1, v2
	v_or_b32_e32 v2, 48, v1
	s_add_u32 s0, s76, s0
	v_add_u32_e32 v5, 0, v146
	v_mul_u32_u24_e32 v7, 0x110, v2
	v_and_b32_e32 v2, 16, v0
	s_addc_u32 s1, s77, s1
	v_lshlrev_b32_e32 v146, 4, v1
	v_cmp_eq_u32_e64 s[10:11], 0, v2
	v_lshl_add_u64 v[2:3], s[0:1], 0, v[146:147]
	s_mov_b64 s[0:1], 0x44b00000
	v_lshrrev_b32_e32 v4, 4, v1
	v_lshl_or_b32 v160, s60, 4, v172
	v_lshl_add_u64 v[154:155], v[2:3], 0, s[0:1]
	v_cndmask_b32_e64 v150, 0, 1.0, s[8:9]
	v_mul_u32_u24_e32 v6, 0x110, v172
	v_lshl_add_u32 v8, v160, 2, 0
	v_mul_u32_u24_e32 v4, 0x840, v4
	s_add_i32 s42, 0, 0x22040
	s_mov_b32 s0, 0x3e2aaaab
	v_mbcnt_lo_u32_b32 v2, -1, 0
	v_add_u32_e32 v163, -3, v185
	v_cmp_lt_u32_e64 s[2:3], 23, v0
	v_add_u32_e32 v164, -2, v185
	v_cmp_lt_u32_e64 s[4:5], 15, v0
	v_add_u32_e32 v165, -1, v185
	v_cmp_lt_u32_e64 s[6:7], 7, v0
	v_cndmask_b32_e64 v166, 0, v185, s[8:9]
	v_mov_b32_e32 v151, v150
	v_mov_b32_e32 v152, v150
	v_mov_b32_e32 v153, v150
	v_cmp_gt_u32_e64 s[12:13], 16, v1
	v_mov_b32_e32 v169, s42
	v_add_u32_e32 v170, v5, v6
	v_add_u32_e32 v171, v5, v7
	v_mov_b32_e32 v185, 0x3ecc95a3
	s_mov_b32 s43, 0x3f317218
	s_mov_b32 s44, 0x7f800000
	s_mov_b32 s45, 0x33800000
	s_mov_b32 s46, 0xbe800000
	s_mov_b32 s1, 0x3e124925
	v_mov_b32_e32 v156, 0x3f317218
	v_mov_b32_e32 v186, 0x7f800000
	v_mov_b32_e32 v187, 0x7fc00000
	v_mov_b32_e32 v188, 0xff800000
	v_add_u32_e32 v189, v8, v4
	v_mbcnt_hi_u32_b32 v190, -1, v2
	s_branch .LBB0_657

.LBB0_657:
	s_mov_b64 s[14:15], exec
	v_readlane_b32 s16, v254, 17
	v_readlane_b32 s17, v254, 18
	s_and_b64 s[16:17], s[14:15], s[16:17]
	s_mov_b64 exec, s[16:17]
	v_readfirstlane_b32 s18, v252
	s_nop 1
	v_add_u32_e32 v161, s18, v253
	v_mov_b32_e32 v2, s42
	ds_write_b32 v2, v161
	s_or_b64 exec, exec, s[14:15]
	s_waitcnt lgkmcnt(0)
	s_barrier
	ds_read_b32 v2, v169
	s_movk_i32 s14, 0x77f
	s_waitcnt lgkmcnt(0)
	v_cmp_lt_i32_e64 s[14:15], s14, v2
	v_readfirstlane_b32 s34, v2
	s_and_b64 vcc, exec, s[14:15]
	s_cbranch_vccnz .LBB0_656
	s_mov_b64 s[16:17], exec
	v_readlane_b32 s18, v254, 17
	v_readlane_b32 s19, v254, 18
	s_and_b64 s[18:19], s[16:17], s[18:19]
	s_mov_b64 exec, s[18:19]
	s_cbranch_execz .LBB0_664
	s_mov_b64 s[20:21], exec
	v_mbcnt_lo_u32_b32 v253, s20, 0
	v_mbcnt_hi_u32_b32 v253, s21, v253
	v_cmp_eq_u32_e32 vcc, 0, v253
	s_and_saveexec_b64 s[18:19], vcc
	s_cbranch_execz .LBB0_663
	s_bcnt1_i32_b64 s20, s[20:21]
	v_mov_b32_e32 v252, s20
	global_atomic_add v252, v147, v252, s[76:77] offset:512 sc0
.LBB0_663:
	s_or_b64 exec, exec, s[18:19]
.LBB0_664:
	s_or_b64 exec, exec, s[16:17]
	s_and_b32 s16, s34, 15
	v_lshl_add_u32 v146, s16, 8, v160
	v_lshlrev_b64 v[2:3], 8, v[146:147]
	s_mov_b32 s29, s94
	s_bfe_u32 s35, s34, 0x60004
	s_ashr_i32 s38, s34, 10
	s_lshl_b32 s18, s16, 7
	v_lshl_add_u64 v[2:3], v[148:149], 0, v[2:3]
	v_readlane_b32 s80, v254, 35
	s_lshl_b32 s17, s35, 6
	v_add_co_u32_e32 v4, vcc, 0x8000, v2
	s_lshl_b32 s16, s38, 12
	v_subrev_u32_e32 v146, s18, v146
	v_readlane_b32 s86, v254, 41
	v_readlane_b32 s87, v254, 42
	v_addc_co_u32_e32 v5, vcc, 0, v3, vcc
	global_load_dwordx4 v[34:37], v[2:3], off
	global_load_dwordx4 v[38:41], v[2:3], off offset:64
	global_load_dwordx4 v[46:49], v[4:5], off
	global_load_dwordx4 v[42:45], v[4:5], off offset:64
	global_load_dwordx4 v[26:29], v[2:3], off offset:128
	global_load_dwordx4 v[14:17], v[2:3], off offset:192
	global_load_dwordx4 v[30:33], v[4:5], off offset:128
	global_load_dwordx4 v[18:21], v[4:5], off offset:192
	s_or_b32 s33, s17, s16
	v_lshlrev_b64 v[2:3], 2, v[146:147]
	v_readlane_b32 s81, v254, 36
	v_readlane_b32 s90, v254, 45
	v_readlane_b32 s91, v254, 46
	s_mov_b64 s[74:75], s[86:87]
	s_mov_b32 s28, s69
	v_readlane_b32 s82, v254, 37
	v_readlane_b32 s83, v254, 38
	v_readlane_b32 s92, v254, 47
	v_readlane_b32 s93, v254, 48
	s_mov_b64 s[68:69], s[80:81]
	s_mov_b64 s[78:79], s[90:91]
	v_lshl_add_u64 v[4:5], s[74:75], 0, v[2:3]
	s_cmp_lg_u32 s35, 0
	s_mov_b64 s[70:71], s[82:83]
	s_mov_b64 s[80:81], s[92:93]
	global_load_dword v192, v[4:5], off
	v_lshl_add_u64 v[4:5], s[78:79], 0, v[2:3]
	s_cselect_b64 s[20:21], -1, 0
	global_load_dword v191, v[4:5], off
	v_lshl_add_u64 v[2:3], s[80:81], 0, v[2:3]
	v_or_b32_e32 v4, s18, v162
	s_or_b64 s[16:17], s[2:3], s[20:21]
	s_or_b64 s[18:19], s[4:5], s[20:21]
	global_load_dword v157, v[2:3], off
	v_lshlrev_b32_e32 v2, 1, v4
	v_mov_b32_e32 v3, v147
	s_and_b64 s[16:17], s[16:17], s[8:9]
	s_and_b64 s[18:19], s[18:19], s[8:9]
	v_lshl_add_u64 v[58:59], s[26:27], 0, v[2:3]
	v_cndmask_b32_e64 v2, 0, v163, s[16:17]
	v_cndmask_b32_e64 v10, 0, v164, s[18:19]
	v_add_u32_e32 v2, s33, v2
	v_add_u32_e32 v10, s33, v10
	v_ashrrev_i32_e32 v3, 31, v2
	v_ashrrev_i32_e32 v11, 31, v10
	v_lshlrev_b32_e32 v82, 2, v4
	v_mov_b32_e32 v83, v147
	v_lshlrev_b64 v[2:3], 12, v[2:3]
	v_lshlrev_b64 v[10:11], 12, v[10:11]
	v_lshl_add_u64 v[62:63], s[68:69], 0, v[82:83]
	v_lshl_add_u64 v[2:3], v[58:59], 0, v[2:3]
	v_lshl_add_u64 v[22:23], v[58:59], 0, v[10:11]
	s_movk_i32 s39, 0x2000
	global_load_dwordx4 v[6:9], v[2:3], off offset:16
	global_load_dwordx4 v[66:69], v[2:3], off
	s_nop 0
	global_load_dwordx4 v[2:5], v82, s[68:69] offset:48
	global_load_dwordx4 v[126:129], v82, s[68:69] offset:32
	global_load_dwordx4 v[106:109], v82, s[68:69] offset:16
	global_load_dwordx4 v[70:73], v82, s[68:69]
	global_load_dwordx4 v[10:13], v[22:23], off offset:16
	global_load_dwordx4 v[74:77], v[22:23], off
	s_mov_b64 s[40:41], 0x2000
	v_add_co_u32_e32 v22, vcc, s39, v62
	s_or_b64 s[20:21], s[6:7], s[20:21]
	v_lshl_add_u64 v[50:51], v[62:63], 0, s[40:41]
	v_addc_co_u32_e32 v23, vcc, 0, v63, vcc
	s_and_b64 s[20:21], s[20:21], s[8:9]
	global_load_dwordx4 v[78:81], v[22:23], off
	s_nop 0
	global_load_dwordx4 v[22:25], v[50:51], off offset:48
	global_load_dwordx4 v[130:133], v[50:51], off offset:32
	global_load_dwordx4 v[110:113], v[50:51], off offset:16
	v_cndmask_b32_e64 v50, 0, v165, s[20:21]
	v_add_u32_e32 v50, s33, v50
	v_ashrrev_i32_e32 v51, 31, v50
	v_lshlrev_b64 v[50:51], 12, v[50:51]
	v_lshl_add_u64 v[54:55], v[58:59], 0, v[50:51]
	s_movk_i32 s39, 0x4000
	global_load_dwordx4 v[50:53], v[54:55], off offset:16
	global_load_dwordx4 v[86:89], v[54:55], off
	s_mov_b64 s[40:41], 0x4000
	v_add_co_u32_e32 v54, vcc, s39, v62
	v_lshl_add_u64 v[60:61], v[62:63], 0, s[40:41]
	s_nop 0
	v_addc_co_u32_e32 v55, vcc, 0, v63, vcc
	global_load_dwordx4 v[90:93], v[54:55], off
	s_nop 0
	global_load_dwordx4 v[54:57], v[60:61], off offset:48
	global_load_dwordx4 v[134:137], v[60:61], off offset:32
	global_load_dwordx4 v[114:117], v[60:61], off offset:16
	v_or_b32_e32 v60, s33, v166
	v_ashrrev_i32_e32 v61, 31, v60
	s_mov_b64 s[40:41], 0x6000
	v_lshlrev_b64 v[60:61], 12, v[60:61]
	v_lshl_add_u64 v[84:85], v[62:63], 0, s[40:41]
	v_add_co_u32_e32 v62, vcc, 0x6000, v62
	v_lshl_add_u64 v[64:65], v[58:59], 0, v[60:61]
	s_nop 0
	v_addc_co_u32_e32 v63, vcc, 0, v63, vcc
	global_load_dwordx4 v[58:61], v[64:65], off offset:16
	global_load_dwordx4 v[94:97], v[64:65], off
	global_load_dwordx4 v[102:105], v[62:63], off
	s_nop 0
	global_load_dwordx4 v[62:65], v[84:85], off offset:48
	global_load_dwordx4 v[138:141], v[84:85], off offset:32
	global_load_dwordx4 v[122:125], v[84:85], off offset:16
	v_lshl_add_u64 v[158:159], s[70:71], 0, v[82:83]
	v_mov_b32_e32 v118, 0
	v_mov_b32_e32 v98, 0
	v_mov_b32_e32 v99, 0
	v_mov_b32_e32 v100, 0
	v_mov_b32_e32 v101, 0
	v_readlane_b32 s84, v254, 39
	v_readlane_b32 s85, v254, 40
	v_readlane_b32 s88, v254, 43
	v_readlane_b32 s89, v254, 44
	v_readlane_b32 s94, v254, 49
	v_readlane_b32 s95, v254, 50
	s_and_saveexec_b64 s[40:41], s[8:9]
	s_cbranch_execz .LBB0_666
	global_load_dwordx4 v[98:101], v[158:159], off
